# phase-0 cooperative-groups grid.sync replaced by a copy of the kernel's XCD-hierarchical grid barrier (on v61)
# baseline (speedup 1.0000x reference)
; #define LAS __attribute__((address_space(3)))
; __device__ __forceinline__ int lane_id_() { int l; asm volatile("v_mbcnt_lo_u32_b32 %0, -1, 0\n\tv_mbcnt_hi_u32_b32 %0, -1, %0" : "=v"(l)); return l; }
; __device__ __forceinline__ unsigned xb_xcc_id() { return (unsigned)__builtin_amdgcn_s_getreg((3 << 11) | 20) & 0xFu; }
; __device__ __forceinline__ void grid_bar(const Ctx& F, unsigned) {
;     asm volatile("s_waitcnt vmcnt(0) lgkmcnt(0)" ::: "memory");
;     __syncthreads();
;     if (F.wid == 0) {
;         if (lane_id_() == 0) {
;             unsigned* bar = (unsigned*)(F.ws + WS_BAR);
;             volatile LAS unsigned* st = (volatile LAS unsigned*)(F.lds + LDS_BYTES - 64);
;             const unsigned x = xb_xcc_id();
;             __builtin_amdgcn_s_waitcnt(0);
;             unsigned nloc = st[0], nx = st[1];
;             if (nloc == 0u) { xcd_barrier_complete(bar, x, nloc, nx); st[0] = nloc; st[1] = nx; }
.LBB0_148:
	s_or_b64 exec, exec, s[8:9]
	s_cmp_eq_u32 s85, 1
	s_cbranch_scc1 .LBB0_160
	s_waitcnt vmcnt(0) lgkmcnt(0)
	s_cmp_lt_u32 s86, 64
	s_barrier
	s_cbranch_scc0 .Lg0_221
	v_mbcnt_lo_u32_b32 v0, -1, 0
	v_mbcnt_hi_u32_b32 v0, -1, v0
	s_nop 0
	v_cmp_eq_u32_e32 vcc, 0, v0
	s_and_saveexec_b64 s[4:5], vcc
	s_cbranch_execz .Lg0_220
	s_add_u32 s6, s46, 0x300200
	s_addc_u32 s7, s47, 0
	s_add_i32 s1, 0, 0x23fc0
	v_mov_b32_e32 v0, s1
	s_getreg_b32 s0, hwreg(HW_REG_XCC_ID, 0, 4)
	s_waitcnt vmcnt(0) expcnt(0) lgkmcnt(0)
	ds_read_b32 v2, v0
	s_add_i32 s1, 0, 0x23fc4
	v_mov_b32_e32 v0, s1
	ds_read_b32 v0, v0
	s_and_b32 s0, s0, 15
	s_waitcnt lgkmcnt(1)
	v_cmp_ne_u32_e32 vcc, 0, v2
	s_cbranch_vccnz .Lg0_184
	s_add_u32 s8, s46, 0x300400
	s_addc_u32 s9, s47, 0
	s_add_u32 s10, s46, 0x300500
	s_addc_u32 s11, s47, 0
	s_add_u32 s12, s46, 0x300600
	s_addc_u32 s13, s47, 0
	s_add_u32 s14, s46, 0x300700
	s_addc_u32 s15, s47, 0
	s_add_u32 s16, s46, 0x300800
	s_addc_u32 s17, s47, 0
	s_add_u32 s18, s46, 0x300900
	s_addc_u32 s19, s47, 0
	s_add_u32 s20, s46, 0x300a00
	s_addc_u32 s21, s47, 0
	s_add_u32 s22, s46, 0x300b00
	s_addc_u32 s23, s47, 0
	s_add_u32 s24, s46, 0x300c00
	s_addc_u32 s25, s47, 0
	s_add_u32 s26, s46, 0x300d00
	s_addc_u32 s27, s47, 0
	s_add_u32 s28, s46, 0x300e00
	s_addc_u32 s29, s47, 0
	s_add_u32 s30, s46, 0x300f00
	s_addc_u32 s31, s47, 0
	s_add_u32 s34, s46, 0x301000
	s_addc_u32 s35, s47, 0
	s_add_u32 s36, s46, 0x301100
	s_addc_u32 s37, s47, 0
	s_add_u32 s38, s46, 0x301200
	s_addc_u32 s39, s47, 0
	s_add_u32 s40, s46, 0x301300
	s_addc_u32 s41, s47, 0
	s_mov_b32 s1, 1
	v_mov_b32_e32 v16, 0
	s_branch .Lg0_172

; __device__ __forceinline__ int lane_id_() { int l; asm volatile("v_mbcnt_lo_u32_b32 %0, -1, 0\n\tv_mbcnt_hi_u32_b32 %0, -1, %0" : "=v"(l)); return l; }
; __device__ __forceinline__ void norm_mod_phase(const Ctx& F, const float* xin, const float* gain, const float* shift, const float* scale) {
;     const int ln = lane_id_();
;     bf16_t* hb = (bf16_t*)(F.ws + WS_HB);
;     const int gw = F.bid * NWAVES + F.wid, NGW = F.G * NWAVES;
;     for (int ch = gw; ch < T / 32; ch += NGW) {
;         const int row0 = ch * 32, b = row0 / S;
;         f32x4 ga[4], sh[4];
; #pragma unroll
;         for (int j = 0; j < 4; ++j) { const int c = 4 * ln + 256 * j; const f32x4 g = *(const f32x4*)(gain + c), sc = *(const f32x4*)(scale + (size_t)b * 6144 + c);
;             ga[j] = g * (sc + 1.0f); sh[j] = *(const f32x4*)(shift + (size_t)b * 6144 + c); }
; __device__ __forceinline__ void grid_bar(const Ctx& F, unsigned) {
;     ...
;     }
;     __syncthreads();
.Lg0_221:
	s_waitcnt lgkmcnt(0)
	s_barrier
.LBB0_160:
	s_cmp_lt_i32 s84, 2
	s_cselect_b64 s[0:1], -1, 0
	s_cmp_gt_i32 s85, 1
	s_cselect_b64 s[4:5], -1, 0
	s_and_b64 s[0:1], s[0:1], s[4:5]
	s_andn2_b64 vcc, exec, s[0:1]
	s_cbranch_vccnz .LBB0_222
	s_lshl_b32 s0, s2, 3
	s_add_i32 s0, s50, s0
	s_mov_b64 s[4:5], s[88:89]
	s_cmpk_lt_i32 s0, 0x800
	v_mbcnt_lo_u32_b32 v0, -1, 0
	v_mbcnt_hi_u32_b32 v0, -1, v0
	s_cbranch_scc0 .LBB0_166
	v_lshlrev_b32_e32 v0, 2, v0
	s_load_dwordx2 s[18:19], s[4:5], 0x0
	s_load_dwordx2 s[6:7], s[4:5], 0x28
	v_ashrrev_i32_e32 v1, 31, v0
	v_lshlrev_b64 v[80:81], 2, v[0:1]
	v_lshl_add_u64 v[84:85], s[46:47], 0, v[80:81]
	s_mov_b64 s[4:5], 0x1000
	v_lshl_add_u64 v[86:87], v[84:85], 0, s[4:5]
	s_lshl_b32 s3, s2, 8
	s_lshl_b32 s4, s50, 5
	s_add_i32 s20, s3, s4
	s_lshl_b32 s1, s90, 3
	s_waitcnt lgkmcnt(0)
	v_lshl_add_u64 v[82:83], s[6:7], 0, v[80:81]
	v_lshlrev_b64 v[88:89], 1, v[0:1]
	s_lshl_b32 s3, s90, 8
	s_or_b32 s22, s20, 3
	s_or_b32 s24, s20, 1
	s_or_b32 s26, s20, 2
	v_mov_b32_e32 v114, 0x6000
	v_mov_b32_e32 v115, 0x358637bd
	s_mov_b32 s33, 0xf800000
	v_mov_b32_e32 v116, 0x260
	s_mov_b32 s42, 0x4200000
